# DF unit epilogue: the queue claim is no longer waited at the exchange barrier (folded into the token after the first gate-load wait)
# speedup vs baseline: 1.0088x; 1.0088x over previous
.LBB0_458:
	v_readlane_b32 s2, v255, 27
	s_waitcnt lgkmcnt(0)
	s_barrier
	v_readlane_b32 s3, v255, 28
	s_andn2_b64 vcc, exec, s[2:3]
	v_readlane_b32 s2, v255, 25
	s_nop 1
	v_lshl_add_u32 v0, v216, 2, s2
	s_cbranch_vccnz .LBB0_460
	v_readlane_b32 s2, v255, 31
	v_mov_b32_e32 v3, v217
	v_mov_b32_e32 v4, v217
	v_mov_b32_e32 v2, s2
	ds_read_b32 v2, v2
	v_permlane32_swap_b32_e32 v3, v4
	v_add_f32_e32 v3, v3, v4
	s_waitcnt lgkmcnt(0)
	v_div_scale_f32 v4, s[2:3], v3, v3, v2
	v_rcp_f32_e32 v5, v4
	s_nop 0
	v_fma_f32 v6, -v4, v5, 1.0
	v_fmac_f32_e32 v5, v6, v5
	v_div_scale_f32 v6, vcc, v2, v3, v2
	v_mul_f32_e32 v7, v6, v5
	v_fma_f32 v8, -v4, v7, v6
	v_fmac_f32_e32 v7, v8, v5
	v_fma_f32 v4, -v4, v7, v6
	v_div_fmas_f32 v4, v4, v5, v7
	v_div_fixup_f32 v2, v4, v3, v2
	v_mul_f32_e32 v3, v64, v2
	v_mul_f32_e32 v4, v65, v2
	ds_write2st64_b32 v0, v3, v4 offset1:1
	v_mul_f32_e32 v3, v66, v2
	v_mul_f32_e32 v4, v67, v2
	ds_write2st64_b32 v0, v3, v4 offset0:2 offset1:3
	v_mul_f32_e32 v3, v68, v2
	v_mul_f32_e32 v4, v69, v2
	ds_write2st64_b32 v0, v3, v4 offset0:4 offset1:5
	v_mul_f32_e32 v3, v70, v2
	v_mul_f32_e32 v4, v71, v2
	ds_write2st64_b32 v0, v3, v4 offset0:6 offset1:7
	v_mul_f32_e32 v3, v72, v2
	v_mul_f32_e32 v4, v73, v2
	ds_write2st64_b32 v0, v3, v4 offset0:8 offset1:9
	v_mul_f32_e32 v3, v74, v2
	v_mul_f32_e32 v4, v75, v2
	ds_write2st64_b32 v0, v3, v4 offset0:10 offset1:11
	v_mul_f32_e32 v3, v76, v2
	v_mul_f32_e32 v4, v77, v2
	ds_write2st64_b32 v0, v3, v4 offset0:12 offset1:13
	v_mul_f32_e32 v3, v78, v2
	v_mul_f32_e32 v4, v79, v2
	ds_write2st64_b32 v0, v3, v4 offset0:14 offset1:15
	v_mul_f32_e32 v3, v48, v2
	v_mul_f32_e32 v4, v49, v2
	ds_write2st64_b32 v0, v3, v4 offset0:16 offset1:17
	v_mul_f32_e32 v3, v50, v2
	v_mul_f32_e32 v4, v51, v2
	ds_write2st64_b32 v0, v3, v4 offset0:18 offset1:19
	v_mul_f32_e32 v3, v52, v2
	v_mul_f32_e32 v4, v53, v2
	ds_write2st64_b32 v0, v3, v4 offset0:20 offset1:21
	v_mul_f32_e32 v3, v54, v2
	v_mul_f32_e32 v4, v55, v2
	ds_write2st64_b32 v0, v3, v4 offset0:22 offset1:23
	v_mul_f32_e32 v3, v56, v2
	v_mul_f32_e32 v4, v57, v2
	ds_write2st64_b32 v0, v3, v4 offset0:24 offset1:25
	v_mul_f32_e32 v3, v58, v2
	v_mul_f32_e32 v4, v59, v2
	ds_write2st64_b32 v0, v3, v4 offset0:26 offset1:27
	v_mul_f32_e32 v3, v60, v2
	v_mul_f32_e32 v4, v61, v2
	ds_write2st64_b32 v0, v3, v4 offset0:28 offset1:29
	v_mul_f32_e32 v3, v62, v2
	v_mul_f32_e32 v4, v63, v2
	ds_write2st64_b32 v0, v3, v4 offset0:30 offset1:31
	v_mul_f32_e32 v3, v32, v2
	v_mul_f32_e32 v4, v33, v2
	ds_write2st64_b32 v0, v3, v4 offset0:32 offset1:33
	v_mul_f32_e32 v3, v34, v2
	v_mul_f32_e32 v4, v35, v2
	ds_write2st64_b32 v0, v3, v4 offset0:34 offset1:35
	v_mul_f32_e32 v3, v36, v2
	v_mul_f32_e32 v4, v37, v2
	ds_write2st64_b32 v0, v3, v4 offset0:36 offset1:37
	v_mul_f32_e32 v3, v38, v2
	v_mul_f32_e32 v4, v39, v2
	ds_write2st64_b32 v0, v3, v4 offset0:38 offset1:39
	v_mul_f32_e32 v3, v40, v2
	v_mul_f32_e32 v4, v41, v2
	ds_write2st64_b32 v0, v3, v4 offset0:40 offset1:41
	v_mul_f32_e32 v3, v42, v2
	v_mul_f32_e32 v4, v43, v2
	ds_write2st64_b32 v0, v3, v4 offset0:42 offset1:43
	v_mul_f32_e32 v3, v44, v2
	v_mul_f32_e32 v4, v45, v2
	ds_write2st64_b32 v0, v3, v4 offset0:44 offset1:45
	v_mul_f32_e32 v3, v46, v2
	v_mul_f32_e32 v4, v47, v2
	ds_write2st64_b32 v0, v3, v4 offset0:46 offset1:47
	v_mul_f32_e32 v3, v16, v2
	v_mul_f32_e32 v4, v17, v2
	ds_write2st64_b32 v0, v3, v4 offset0:48 offset1:49
	v_mul_f32_e32 v3, v18, v2
	v_mul_f32_e32 v4, v19, v2
	ds_write2st64_b32 v0, v3, v4 offset0:50 offset1:51
	v_mul_f32_e32 v3, v20, v2
	v_mul_f32_e32 v4, v21, v2
	ds_write2st64_b32 v0, v3, v4 offset0:52 offset1:53
	v_mul_f32_e32 v3, v22, v2
	v_mul_f32_e32 v4, v23, v2
	ds_write2st64_b32 v0, v3, v4 offset0:54 offset1:55
	v_mul_f32_e32 v3, v24, v2
	v_mul_f32_e32 v4, v25, v2
	ds_write2st64_b32 v0, v3, v4 offset0:56 offset1:57
	v_mul_f32_e32 v3, v26, v2
	v_mul_f32_e32 v4, v27, v2
	ds_write2st64_b32 v0, v3, v4 offset0:58 offset1:59
	v_mul_f32_e32 v3, v28, v2
	v_mul_f32_e32 v4, v29, v2
	ds_write2st64_b32 v0, v3, v4 offset0:60 offset1:61
	v_mul_f32_e32 v3, v30, v2
	v_mul_f32_e32 v2, v31, v2
	ds_write2st64_b32 v0, v3, v2 offset0:62 offset1:63
.LBB0_460:
	s_waitcnt lgkmcnt(0)
	s_barrier
	s_and_b64 vcc, exec, s[4:5]
	s_cbranch_vccnz .LBB0_299
	v_mov_b32_e32 v2, v217
	s_nop 1
	v_permlane32_swap_b32_e32 v217, v2
	v_add_f32_e32 v2, v217, v2
	v_div_scale_f32 v3, s[2:3], v2, v2, 1.0
	v_rcp_f32_e32 v4, v3
	s_waitcnt vmcnt(3)
	v_min_u32_e32 v253, 0xffff, v253
	v_or_b32_e32 v95, v95, v253
	v_lshlrev_b32_e32 v110, 16, v107
	v_and_b32_e32 v111, 0xffff0000, v107
	s_lshl_b64 s[2:3], s[6:7], 22
	v_fma_f32 v5, -v3, v4, 1.0
	v_fmac_f32_e32 v4, v5, v4
	v_div_scale_f32 v5, vcc, 1.0, v2, 1.0
	v_mul_f32_e32 v6, v5, v4
	v_fma_f32 v7, -v3, v6, v5
	v_fmac_f32_e32 v6, v7, v4
	v_fma_f32 v3, -v3, v6, v5
	v_div_fmas_f32 v3, v3, v4, v6
	v_div_fixup_f32 v94, v3, v2, 1.0
	ds_read2st64_b32 v[100:101], v0 offset1:1
	ds_read2st64_b32 v[98:99], v0 offset0:2 offset1:3
	ds_read2st64_b32 v[112:113], v0 offset0:4 offset1:5
	ds_read2st64_b32 v[108:109], v0 offset0:6 offset1:7
	ds_read2st64_b32 v[124:125], v0 offset0:8 offset1:9
	ds_read2st64_b32 v[128:129], v0 offset0:10 offset1:11
	ds_read2st64_b32 v[138:139], v0 offset0:12 offset1:13
	ds_read2st64_b32 v[186:187], v0 offset0:14 offset1:15
	ds_read2st64_b32 v[140:141], v0 offset0:16 offset1:17
	ds_read2st64_b32 v[136:137], v0 offset0:18 offset1:19
	ds_read2st64_b32 v[188:189], v0 offset0:20 offset1:21
	ds_read2st64_b32 v[194:195], v0 offset0:22 offset1:23
	ds_read2st64_b32 v[200:201], v0 offset0:24 offset1:25
	ds_read2st64_b32 v[192:193], v0 offset0:26 offset1:27
	ds_read2st64_b32 v[210:211], v0 offset0:28 offset1:29
	ds_read2st64_b32 v[202:203], v0 offset0:30 offset1:31
	ds_read2st64_b32 v[216:217], v0 offset0:32 offset1:33
	ds_read2st64_b32 v[212:213], v0 offset0:34 offset1:35
	ds_read2st64_b32 v[204:205], v0 offset0:36 offset1:37
	ds_read2st64_b32 v[208:209], v0 offset0:38 offset1:39
	ds_read2st64_b32 v[190:191], v0 offset0:40 offset1:41
	ds_read2st64_b32 v[198:199], v0 offset0:42 offset1:43
	ds_read2st64_b32 v[180:181], v0 offset0:44 offset1:45
	ds_read2st64_b32 v[182:183], v0 offset0:46 offset1:47
	ds_read2st64_b32 v[114:115], v0 offset0:56 offset1:57
	ds_read2st64_b32 v[116:117], v0 offset0:58 offset1:59
	ds_read2st64_b32 v[102:103], v0 offset0:60 offset1:61
	ds_read2st64_b32 v[2:3], v0 offset0:62 offset1:63
	ds_read2st64_b32 v[142:143], v0 offset0:48 offset1:49
	ds_read2st64_b32 v[144:145], v0 offset0:50 offset1:51
	ds_read2st64_b32 v[126:127], v0 offset0:52 offset1:53
	ds_read2st64_b32 v[130:131], v0 offset0:54 offset1:55
	s_waitcnt lgkmcnt(14)
	v_pk_fma_f32 v[100:101], v[64:65], v[94:95], v[100:101] op_sel_hi:[1,0,1] neg_lo:[0,0,1] neg_hi:[0,0,1]
	v_lshlrev_b32_e32 v64, 16, v106
	s_waitcnt lgkmcnt(4)
	v_pk_fma_f32 v[86:87], v[30:31], v[94:95], v[2:3] op_sel_hi:[1,0,1] neg_lo:[0,0,1] neg_hi:[0,0,1]
	v_and_b32_e32 v65, 0xffff0000, v106
	v_mul_f32_e32 v31, 0xbfb8aa3b, v64
	v_pk_fma_f32 v[98:99], v[66:67], v[94:95], v[98:99] op_sel_hi:[1,0,1] neg_lo:[0,0,1] neg_hi:[0,0,1]
	v_exp_f32_e32 v66, v31
	v_mul_f32_e32 v31, 0xbfb8aa3b, v65
	v_exp_f32_e32 v67, v31
	v_mul_f32_e32 v106, 0xbfb8aa3b, v110
	v_add_f32_e32 v66, 1.0, v66
	v_exp_f32_e32 v118, v106
	v_add_f32_e32 v67, 1.0, v67
	v_mul_f32_e32 v106, 0xbfb8aa3b, v111
	v_rcp_f32_e32 v66, v66
	v_rcp_f32_e32 v67, v67
	v_exp_f32_e32 v119, v106
	v_mul_f32_e32 v30, v101, v101
	v_pk_fma_f32 v[30:31], v[100:101], v[100:101], v[30:31] op_sel_hi:[1,1,0]
	v_pk_mul_f32 v[106:107], v[66:67], v[64:65]
	v_add_f32_e32 v64, 1.0, v118
	v_add_f32_e32 v65, 1.0, v119
	v_rcp_f32_e32 v64, v64
	v_rcp_f32_e32 v65, v65
	v_pk_fma_f32 v[30:31], v[98:99], v[98:99], v[30:31]
	v_mul_f32_e32 v66, v99, v99
	v_pk_add_f32 v[30:31], v[66:67], v[30:31] op_sel_hi:[0,1]
	v_lshlrev_b32_e32 v66, 16, v12
	v_and_b32_e32 v67, 0xffff0000, v12
	v_mul_f32_e32 v12, 0xbfb8aa3b, v66
	v_pk_mul_f32 v[110:111], v[64:65], v[110:111]
	v_exp_f32_e32 v12, v12
	v_mul_f32_e32 v65, 0xbfb8aa3b, v67
	v_exp_f32_e32 v65, v65
	v_pk_fma_f32 v[112:113], v[68:69], v[94:95], v[112:113] op_sel_hi:[1,0,1] neg_lo:[0,0,1] neg_hi:[0,0,1]
	v_add_f32_e32 v12, 1.0, v12
	v_pk_fma_f32 v[30:31], v[112:113], v[112:113], v[30:31]
	v_mul_f32_e32 v64, v113, v113
	v_pk_add_f32 v[30:31], v[64:65], v[30:31] op_sel_hi:[0,1]
	v_rcp_f32_e32 v64, v12
	v_add_f32_e32 v12, 1.0, v65
	v_rcp_f32_e32 v65, v12
	v_lshlrev_b32_e32 v12, 16, v13
	v_and_b32_e32 v13, 0xffff0000, v13
	v_mul_f32_e32 v68, 0xbfb8aa3b, v12
	v_mul_f32_e32 v69, 0xbfb8aa3b, v13
	v_exp_f32_e32 v68, v68
	v_exp_f32_e32 v69, v69
	v_pk_mul_f32 v[118:119], v[64:65], v[66:67]
	v_pk_fma_f32 v[108:109], v[70:71], v[94:95], v[108:109] op_sel_hi:[1,0,1] neg_lo:[0,0,1] neg_hi:[0,0,1]
	v_add_f32_e32 v64, 1.0, v68
	v_add_f32_e32 v65, 1.0, v69
	v_rcp_f32_e32 v64, v64
	v_rcp_f32_e32 v65, v65
	v_pk_fma_f32 v[30:31], v[108:109], v[108:109], v[30:31]
	v_mul_f32_e32 v66, v109, v109
	v_pk_add_f32 v[30:31], v[66:67], v[30:31] op_sel_hi:[0,1]
	v_pk_mul_f32 v[122:123], v[64:65], v[12:13]
	v_lshlrev_b32_e32 v64, 16, v10
	v_pk_fma_f32 v[72:73], v[72:73], v[94:95], v[124:125] op_sel_hi:[1,0,1] neg_lo:[0,0,1] neg_hi:[0,0,1]
	v_and_b32_e32 v65, 0xffff0000, v10
	v_mul_f32_e32 v10, 0xbfb8aa3b, v64
	v_pk_fma_f32 v[12:13], v[72:73], v[72:73], v[30:31]
	v_exp_f32_e32 v10, v10
	v_mul_f32_e32 v31, 0xbfb8aa3b, v65
	v_exp_f32_e32 v31, v31
	v_mul_f32_e32 v30, v73, v73
	v_add_f32_e32 v10, 1.0, v10
	v_pk_fma_f32 v[74:75], v[74:75], v[94:95], v[128:129] op_sel_hi:[1,0,1] neg_lo:[0,0,1] neg_hi:[0,0,1]
	v_pk_add_f32 v[12:13], v[30:31], v[12:13] op_sel_hi:[0,1]
	v_rcp_f32_e32 v30, v10
	v_add_f32_e32 v10, 1.0, v31
	v_rcp_f32_e32 v31, v10
	v_lshlrev_b32_e32 v10, 16, v11
	v_and_b32_e32 v11, 0xffff0000, v11
	v_mul_f32_e32 v66, 0xbfb8aa3b, v10
	v_mul_f32_e32 v67, 0xbfb8aa3b, v11
	v_exp_f32_e32 v66, v66
	v_exp_f32_e32 v67, v67
	v_pk_mul_f32 v[124:125], v[30:31], v[64:65]
	v_pk_fma_f32 v[12:13], v[74:75], v[74:75], v[12:13]
	v_add_f32_e32 v30, 1.0, v66
	v_add_f32_e32 v31, 1.0, v67
	v_rcp_f32_e32 v30, v30
	v_rcp_f32_e32 v31, v31
	v_mul_f32_e32 v64, v75, v75
	v_pk_add_f32 v[68:69], v[64:65], v[12:13] op_sel_hi:[0,1]
	v_pk_fma_f32 v[76:77], v[76:77], v[94:95], v[138:139] op_sel_hi:[1,0,1] neg_lo:[0,0,1] neg_hi:[0,0,1]
	v_lshlrev_b32_e32 v70, 16, v134
	v_and_b32_e32 v71, 0xffff0000, v134
	v_pk_mul_f32 v[128:129], v[30:31], v[10:11]
	v_pk_fma_f32 v[30:31], v[76:77], v[76:77], v[68:69]
	v_mul_f32_e32 v69, 0xbfb8aa3b, v70
	v_mul_f32_e32 v134, 0xbfb8aa3b, v71
	v_exp_f32_e32 v69, v69
	v_exp_f32_e32 v134, v134
	v_mul_f32_e32 v68, v77, v77
	v_lshlrev_b32_e32 v138, 16, v135
	v_pk_add_f32 v[30:31], v[68:69], v[30:31] op_sel_hi:[0,1]
	v_add_f32_e32 v68, 1.0, v69
	v_add_f32_e32 v69, 1.0, v134
	v_and_b32_e32 v139, 0xffff0000, v135
	v_mul_f32_e32 v134, 0xbfb8aa3b, v138
	v_exp_f32_e32 v148, v134
	v_mul_f32_e32 v134, 0xbfb8aa3b, v139
	v_rcp_f32_e32 v68, v68
	v_rcp_f32_e32 v69, v69
	v_exp_f32_e32 v149, v134
	v_pk_fma_f32 v[136:137], v[50:51], v[94:95], v[136:137] op_sel_hi:[1,0,1] neg_lo:[0,0,1] neg_hi:[0,0,1]
	v_lshlrev_b32_e32 v50, 16, v184
	v_pk_mul_f32 v[134:135], v[68:69], v[70:71]
	v_add_f32_e32 v68, 1.0, v148
	v_add_f32_e32 v69, 1.0, v149
	v_rcp_f32_e32 v68, v68
	v_rcp_f32_e32 v69, v69
	v_and_b32_e32 v51, 0xffff0000, v184
	v_pk_fma_f32 v[140:141], v[48:49], v[94:95], v[140:141] op_sel_hi:[1,0,1] neg_lo:[0,0,1] neg_hi:[0,0,1]
	v_mul_f32_e32 v49, 0xbfb8aa3b, v50
	v_pk_mul_f32 v[138:139], v[68:69], v[138:139]
	v_mul_f32_e32 v68, 0xbfb8aa3b, v51
	v_pk_fma_f32 v[78:79], v[78:79], v[94:95], v[186:187] op_sel_hi:[1,0,1] neg_lo:[0,0,1] neg_hi:[0,0,1]
	v_exp_f32_e32 v49, v49
	v_exp_f32_e32 v68, v68
	v_pk_fma_f32 v[30:31], v[78:79], v[78:79], v[30:31]
	v_mul_f32_e32 v70, v79, v79
	v_pk_add_f32 v[30:31], v[70:71], v[30:31] op_sel_hi:[0,1]
	v_pk_fma_f32 v[30:31], v[140:141], v[140:141], v[30:31]
	v_mul_f32_e32 v48, v141, v141
	v_pk_add_f32 v[30:31], v[48:49], v[30:31] op_sel_hi:[0,1]
	v_add_f32_e32 v48, 1.0, v49
	v_add_f32_e32 v49, 1.0, v68
	v_lshlrev_b32_e32 v0, 11, v179
	v_rcp_f32_e32 v48, v48
	v_rcp_f32_e32 v49, v49
	v_lshl_add_u64 v[2:3], s[56:57], 0, v[0:1]
	v_lshlrev_b32_e32 v68, 16, v185
	v_and_b32_e32 v69, 0xffff0000, v185
	v_pk_fma_f32 v[184:185], v[54:55], v[94:95], v[194:195] op_sel_hi:[1,0,1] neg_lo:[0,0,1] neg_hi:[0,0,1]
	v_lshlrev_b32_e32 v54, 16, v146
	v_and_b32_e32 v55, 0xffff0000, v146
	v_lshl_add_u64 v[2:3], v[2:3], 0, s[2:3]
	s_lshl_b32 s80, s16, 8
	v_pk_fma_f32 v[188:189], v[52:53], v[94:95], v[188:189] op_sel_hi:[1,0,1] neg_lo:[0,0,1] neg_hi:[0,0,1]
	v_mul_f32_e32 v53, 0xbfb8aa3b, v54
	v_mul_f32_e32 v146, 0xbfb8aa3b, v55
	v_lshl_add_u64 v[2:3], v[2:3], 0, s[80:81]
	v_ashrrev_i32_e32 v179, 31, v178
	v_exp_f32_e32 v53, v53
	v_exp_f32_e32 v146, v146
	v_lshl_add_u64 v[88:89], v[178:179], 1, v[2:3]
	v_lshl_add_u32 v0, v178, 2, 0
	v_pk_mul_f32 v[178:179], v[48:49], v[50:51]
	v_pk_fma_f32 v[30:31], v[136:137], v[136:137], v[30:31]
	v_mul_f32_e32 v50, v137, v137
	v_pk_add_f32 v[30:31], v[50:51], v[30:31] op_sel_hi:[0,1]
	v_pk_fma_f32 v[30:31], v[188:189], v[188:189], v[30:31]
	v_mul_f32_e32 v52, v189, v189
	v_lshlrev_b32_e32 v148, 16, v147
	v_pk_add_f32 v[30:31], v[52:53], v[30:31] op_sel_hi:[0,1]
	v_add_f32_e32 v52, 1.0, v53
	v_add_f32_e32 v53, 1.0, v146
	v_and_b32_e32 v149, 0xffff0000, v147
	v_mul_f32_e32 v146, 0xbfb8aa3b, v148
	v_exp_f32_e32 v150, v146
	v_mul_f32_e32 v146, 0xbfb8aa3b, v149
	v_rcp_f32_e32 v52, v52
	v_rcp_f32_e32 v53, v53
	v_exp_f32_e32 v151, v146
	v_pk_fma_f32 v[30:31], v[184:185], v[184:185], v[30:31]
	v_pk_fma_f32 v[200:201], v[56:57], v[94:95], v[200:201] op_sel_hi:[1,0,1] neg_lo:[0,0,1] neg_hi:[0,0,1]
	v_pk_mul_f32 v[146:147], v[52:53], v[54:55]
	v_add_f32_e32 v52, 1.0, v150
	v_add_f32_e32 v53, 1.0, v151
	v_rcp_f32_e32 v52, v52
	v_rcp_f32_e32 v53, v53
	v_mul_f32_e32 v54, v185, v185
	v_pk_add_f32 v[30:31], v[54:55], v[30:31] op_sel_hi:[0,1]
	v_lshlrev_b32_e32 v54, 16, v132
	v_and_b32_e32 v55, 0xffff0000, v132
	v_pk_mul_f32 v[194:195], v[52:53], v[148:149]
	v_mul_f32_e32 v53, 0xbfb8aa3b, v54
	v_mul_f32_e32 v56, 0xbfb8aa3b, v55
	v_exp_f32_e32 v53, v53
	v_exp_f32_e32 v56, v56
	v_pk_fma_f32 v[30:31], v[200:201], v[200:201], v[30:31]
	v_mul_f32_e32 v52, v201, v201
	v_pk_add_f32 v[30:31], v[52:53], v[30:31] op_sel_hi:[0,1]
	v_add_f32_e32 v52, 1.0, v53
	v_add_f32_e32 v53, 1.0, v56
	v_rcp_f32_e32 v52, v52
	v_rcp_f32_e32 v53, v53
	v_pk_fma_f32 v[202:203], v[62:63], v[94:95], v[202:203] op_sel_hi:[1,0,1] neg_lo:[0,0,1] neg_hi:[0,0,1]
	v_lshlrev_b32_e32 v62, 16, v120
	v_and_b32_e32 v63, 0xffff0000, v120
	v_pk_fma_f32 v[210:211], v[60:61], v[94:95], v[210:211] op_sel_hi:[1,0,1] neg_lo:[0,0,1] neg_hi:[0,0,1]
	v_mul_f32_e32 v61, 0xbfb8aa3b, v62
	v_mul_f32_e32 v120, 0xbfb8aa3b, v63
	v_pk_fma_f32 v[192:193], v[58:59], v[94:95], v[192:193] op_sel_hi:[1,0,1] neg_lo:[0,0,1] neg_hi:[0,0,1]
	v_exp_f32_e32 v61, v61
	v_exp_f32_e32 v120, v120
	v_lshlrev_b32_e32 v56, 16, v133
	v_and_b32_e32 v57, 0xffff0000, v133
	v_pk_mul_f32 v[132:133], v[52:53], v[54:55]
	v_pk_fma_f32 v[30:31], v[192:193], v[192:193], v[30:31]
	v_mul_f32_e32 v54, v193, v193
	v_pk_add_f32 v[30:31], v[54:55], v[30:31] op_sel_hi:[0,1]
	v_pk_fma_f32 v[30:31], v[210:211], v[210:211], v[30:31]
	v_mul_f32_e32 v60, v211, v211
	v_lshlrev_b32_e32 v148, 16, v121
	v_pk_add_f32 v[30:31], v[60:61], v[30:31] op_sel_hi:[0,1]
	v_add_f32_e32 v60, 1.0, v61
	v_add_f32_e32 v61, 1.0, v120
	v_and_b32_e32 v149, 0xffff0000, v121
	v_mul_f32_e32 v120, 0xbfb8aa3b, v148
	v_exp_f32_e32 v150, v120
	v_mul_f32_e32 v120, 0xbfb8aa3b, v149
	v_rcp_f32_e32 v60, v60
	v_rcp_f32_e32 v61, v61
	v_exp_f32_e32 v151, v120
	v_pk_fma_f32 v[212:213], v[34:35], v[94:95], v[212:213] op_sel_hi:[1,0,1] neg_lo:[0,0,1] neg_hi:[0,0,1]
	v_lshlrev_b32_e32 v34, 16, v104
	v_pk_mul_f32 v[120:121], v[60:61], v[62:63]
	v_add_f32_e32 v60, 1.0, v150
	v_add_f32_e32 v61, 1.0, v151
	v_rcp_f32_e32 v60, v60
	v_rcp_f32_e32 v61, v61
	v_and_b32_e32 v35, 0xffff0000, v104
	v_pk_fma_f32 v[216:217], v[32:33], v[94:95], v[216:217] op_sel_hi:[1,0,1] neg_lo:[0,0,1] neg_hi:[0,0,1]
	v_mul_f32_e32 v33, 0xbfb8aa3b, v34
	v_pk_mul_f32 v[214:215], v[60:61], v[148:149]
	v_mul_f32_e32 v60, 0xbfb8aa3b, v35
	v_exp_f32_e32 v33, v33
	v_exp_f32_e32 v60, v60
	v_pk_fma_f32 v[30:31], v[202:203], v[202:203], v[30:31]
	v_mul_f32_e32 v62, v203, v203
	v_pk_add_f32 v[30:31], v[62:63], v[30:31] op_sel_hi:[0,1]
	v_pk_fma_f32 v[30:31], v[216:217], v[216:217], v[30:31]
	v_mul_f32_e32 v32, v217, v217
	v_pk_add_f32 v[30:31], v[32:33], v[30:31] op_sel_hi:[0,1]
	v_add_f32_e32 v32, 1.0, v33
	v_add_f32_e32 v33, 1.0, v60
	v_rcp_f32_e32 v32, v32
	v_rcp_f32_e32 v33, v33
	v_pk_fma_f32 v[208:209], v[38:39], v[94:95], v[208:209] op_sel_hi:[1,0,1] neg_lo:[0,0,1] neg_hi:[0,0,1]
	v_lshlrev_b32_e32 v38, 16, v96
	v_and_b32_e32 v39, 0xffff0000, v96
	v_pk_fma_f32 v[204:205], v[36:37], v[94:95], v[204:205] op_sel_hi:[1,0,1] neg_lo:[0,0,1] neg_hi:[0,0,1]
	v_mul_f32_e32 v37, 0xbfb8aa3b, v38
	v_mul_f32_e32 v96, 0xbfb8aa3b, v39
	v_exp_f32_e32 v37, v37
	v_exp_f32_e32 v96, v96
	v_lshlrev_b32_e32 v60, 16, v105
	v_and_b32_e32 v61, 0xffff0000, v105
	v_pk_mul_f32 v[104:105], v[32:33], v[34:35]
	v_pk_fma_f32 v[30:31], v[212:213], v[212:213], v[30:31]
	v_mul_f32_e32 v34, v213, v213
	v_pk_add_f32 v[34:35], v[34:35], v[30:31] op_sel_hi:[0,1]
	v_pk_fma_f32 v[34:35], v[204:205], v[204:205], v[34:35]
	v_mul_f32_e32 v36, v205, v205
	v_lshlrev_b32_e32 v148, 16, v97
	v_pk_add_f32 v[34:35], v[36:37], v[34:35] op_sel_hi:[0,1]
	v_add_f32_e32 v36, 1.0, v37
	v_add_f32_e32 v37, 1.0, v96
	v_and_b32_e32 v149, 0xffff0000, v97
	v_mul_f32_e32 v96, 0xbfb8aa3b, v148
	v_exp_f32_e32 v150, v96
	v_mul_f32_e32 v96, 0xbfb8aa3b, v149
	v_rcp_f32_e32 v36, v36
	v_rcp_f32_e32 v37, v37
	v_exp_f32_e32 v151, v96
	v_pk_fma_f32 v[34:35], v[208:209], v[208:209], v[34:35]
	v_pk_fma_f32 v[190:191], v[40:41], v[94:95], v[190:191] op_sel_hi:[1,0,1] neg_lo:[0,0,1] neg_hi:[0,0,1]
	v_pk_mul_f32 v[96:97], v[36:37], v[38:39]
	v_add_f32_e32 v36, 1.0, v150
	v_add_f32_e32 v37, 1.0, v151
	v_rcp_f32_e32 v36, v36
	v_rcp_f32_e32 v37, v37
	v_mul_f32_e32 v38, v209, v209
	v_pk_add_f32 v[34:35], v[38:39], v[34:35] op_sel_hi:[0,1]
	v_lshlrev_b32_e32 v38, 16, v92
	v_and_b32_e32 v39, 0xffff0000, v92
	v_pk_mul_f32 v[220:221], v[36:37], v[148:149]
	v_mul_f32_e32 v37, 0xbfb8aa3b, v38
	v_mul_f32_e32 v40, 0xbfb8aa3b, v39
	v_exp_f32_e32 v37, v37
	v_exp_f32_e32 v40, v40
	v_pk_fma_f32 v[34:35], v[190:191], v[190:191], v[34:35]
	v_mul_f32_e32 v36, v191, v191
	v_pk_add_f32 v[34:35], v[36:37], v[34:35] op_sel_hi:[0,1]
	v_add_f32_e32 v36, 1.0, v37
	v_add_f32_e32 v37, 1.0, v40
	v_lshlrev_b32_e32 v40, 16, v93
	v_and_b32_e32 v41, 0xffff0000, v93
	v_pk_fma_f32 v[198:199], v[42:43], v[94:95], v[198:199] op_sel_hi:[1,0,1] neg_lo:[0,0,1] neg_hi:[0,0,1]
	v_rcp_f32_e32 v36, v36
	v_rcp_f32_e32 v37, v37
	v_mul_f32_e32 v42, 0xbfb8aa3b, v40
	v_mul_f32_e32 v43, 0xbfb8aa3b, v41
	v_exp_f32_e32 v42, v42
	v_exp_f32_e32 v43, v43
	v_lshlrev_b32_e32 v148, 16, v90
	v_and_b32_e32 v149, 0xffff0000, v90
	v_pk_fma_f32 v[180:181], v[44:45], v[94:95], v[180:181] op_sel_hi:[1,0,1] neg_lo:[0,0,1] neg_hi:[0,0,1]
	v_mul_f32_e32 v45, 0xbfb8aa3b, v148
	v_mul_f32_e32 v90, 0xbfb8aa3b, v149
	v_exp_f32_e32 v45, v45
	v_exp_f32_e32 v90, v90
	v_pk_mul_f32 v[92:93], v[36:37], v[38:39]
	v_pk_fma_f32 v[34:35], v[198:199], v[198:199], v[34:35]
	v_mul_f32_e32 v38, v199, v199
	v_add_f32_e32 v36, 1.0, v42
	v_add_f32_e32 v37, 1.0, v43
	v_pk_add_f32 v[42:43], v[38:39], v[34:35] op_sel_hi:[0,1]
	v_pk_fma_f32 v[42:43], v[180:181], v[180:181], v[42:43]
	v_mul_f32_e32 v44, v181, v181
	v_lshlrev_b32_e32 v150, 16, v91
	v_pk_add_f32 v[42:43], v[44:45], v[42:43] op_sel_hi:[0,1]
	v_add_f32_e32 v44, 1.0, v45
	v_add_f32_e32 v45, 1.0, v90
	v_and_b32_e32 v151, 0xffff0000, v91
	v_mul_f32_e32 v90, 0xbfb8aa3b, v150
	v_pk_fma_f32 v[46:47], v[46:47], v[94:95], v[182:183] op_sel_hi:[1,0,1] neg_lo:[0,0,1] neg_hi:[0,0,1]
	v_exp_f32_e32 v182, v90
	v_mul_f32_e32 v90, 0xbfb8aa3b, v151
	v_rcp_f32_e32 v44, v44
	v_rcp_f32_e32 v45, v45
	v_exp_f32_e32 v183, v90
	v_pk_fma_f32 v[42:43], v[46:47], v[46:47], v[42:43]
	s_waitcnt lgkmcnt(3)
	v_pk_fma_f32 v[142:143], v[16:17], v[94:95], v[142:143] op_sel_hi:[1,0,1] neg_lo:[0,0,1] neg_hi:[0,0,1]
	v_pk_mul_f32 v[90:91], v[44:45], v[148:149]
	v_add_f32_e32 v44, 1.0, v182
	v_add_f32_e32 v45, 1.0, v183
	v_rcp_f32_e32 v44, v44
	v_rcp_f32_e32 v45, v45
	v_mul_f32_e32 v148, v47, v47
	v_pk_add_f32 v[42:43], v[148:149], v[42:43] op_sel_hi:[0,1]
	v_pk_fma_f32 v[16:17], v[142:143], v[142:143], v[42:43]
	v_pk_mul_f32 v[182:183], v[44:45], v[150:151]
	v_lshlrev_b32_e32 v44, 16, v14
	v_and_b32_e32 v45, 0xffff0000, v14
	v_mul_f32_e32 v14, 0xbfb8aa3b, v44
	v_exp_f32_e32 v14, v14
	v_mul_f32_e32 v43, 0xbfb8aa3b, v45
	v_exp_f32_e32 v43, v43
	v_mul_f32_e32 v42, v143, v143
	v_add_f32_e32 v14, 1.0, v14
	s_waitcnt lgkmcnt(2)
	v_pk_fma_f32 v[18:19], v[18:19], v[94:95], v[144:145] op_sel_hi:[1,0,1] neg_lo:[0,0,1] neg_hi:[0,0,1]
	v_pk_add_f32 v[16:17], v[42:43], v[16:17] op_sel_hi:[0,1]
	v_rcp_f32_e32 v42, v14
	v_add_f32_e32 v14, 1.0, v43
	v_rcp_f32_e32 v43, v14
	v_lshlrev_b32_e32 v14, 16, v15
	v_and_b32_e32 v15, 0xffff0000, v15
	v_mul_f32_e32 v144, 0xbfb8aa3b, v14
	v_exp_f32_e32 v148, v144
	v_mul_f32_e32 v144, 0xbfb8aa3b, v15
	v_exp_f32_e32 v149, v144
	v_pk_mul_f32 v[144:145], v[42:43], v[44:45]
	v_pk_fma_f32 v[16:17], v[18:19], v[18:19], v[16:17]
	v_mul_f32_e32 v44, v19, v19
	v_add_f32_e32 v42, 1.0, v148
	v_add_f32_e32 v43, 1.0, v149
	v_pk_add_f32 v[148:149], v[44:45], v[16:17] op_sel_hi:[0,1]
	s_waitcnt lgkmcnt(1)
	v_pk_fma_f32 v[20:21], v[20:21], v[94:95], v[126:127] op_sel_hi:[1,0,1] neg_lo:[0,0,1] neg_hi:[0,0,1]
	s_waitcnt lgkmcnt(0)
	v_pk_fma_f32 v[22:23], v[22:23], v[94:95], v[130:131] op_sel_hi:[1,0,1] neg_lo:[0,0,1] neg_hi:[0,0,1]
	v_pk_fma_f32 v[126:127], v[20:21], v[20:21], v[148:149]
	s_waitcnt vmcnt(2)
	v_lshlrev_b32_e32 v148, 16, v84
	v_and_b32_e32 v149, 0xffff0000, v84
	v_mul_f32_e32 v84, 0xbfb8aa3b, v148
	v_exp_f32_e32 v84, v84
	v_mul_f32_e32 v131, 0xbfb8aa3b, v149
	v_exp_f32_e32 v131, v131
	v_mul_f32_e32 v130, v21, v21
	v_add_f32_e32 v84, 1.0, v84
	v_lshlrev_b32_e32 v150, 16, v85
	v_pk_add_f32 v[126:127], v[130:131], v[126:127] op_sel_hi:[0,1]
	v_rcp_f32_e32 v130, v84
	v_add_f32_e32 v84, 1.0, v131
	v_rcp_f32_e32 v131, v84
	v_and_b32_e32 v151, 0xffff0000, v85
	v_mul_f32_e32 v84, 0xbfb8aa3b, v150
	v_exp_f32_e32 v233, v84
	v_mul_f32_e32 v84, 0xbfb8aa3b, v151
	v_exp_f32_e32 v234, v84
	v_pk_mul_f32 v[84:85], v[130:131], v[148:149]
	v_add_f32_e32 v130, 1.0, v233
	v_rcp_f32_e32 v130, v130
	v_add_f32_e32 v131, 1.0, v234
	v_rcp_f32_e32 v131, v131
	v_pk_fma_f32 v[26:27], v[26:27], v[94:95], v[116:117] op_sel_hi:[1,0,1] neg_lo:[0,0,1] neg_hi:[0,0,1]
	s_waitcnt vmcnt(1)
	v_lshlrev_b32_e32 v116, 16, v82
	v_pk_fma_f32 v[126:127], v[22:23], v[22:23], v[126:127]
	v_mul_f32_e32 v148, v23, v23
	v_and_b32_e32 v117, 0xffff0000, v82
	v_mul_f32_e32 v82, 0xbfb8aa3b, v116
	v_pk_add_f32 v[148:149], v[148:149], v[126:127] op_sel_hi:[0,1]
	v_pk_mul_f32 v[126:127], v[130:131], v[150:151]
	v_exp_f32_e32 v82, v82
	v_mul_f32_e32 v130, 0xbfb8aa3b, v117
	v_exp_f32_e32 v130, v130
	v_pk_fma_f32 v[24:25], v[24:25], v[94:95], v[114:115] op_sel_hi:[1,0,1] neg_lo:[0,0,1] neg_hi:[0,0,1]
	v_add_f32_e32 v82, 1.0, v82
	v_rcp_f32_e32 v114, v82
	v_add_f32_e32 v82, 1.0, v130
	v_rcp_f32_e32 v115, v82
	v_pk_fma_f32 v[130:131], v[24:25], v[24:25], v[148:149]
	v_mul_f32_e32 v82, v25, v25
	v_pk_add_f32 v[130:131], v[82:83], v[130:131] op_sel_hi:[0,1]
	v_lshlrev_b32_e32 v82, 16, v83
	v_pk_mul_f32 v[234:235], v[114:115], v[116:117]
	v_mul_f32_e32 v116, 0xbfb8aa3b, v82
	v_exp_f32_e32 v117, v116
	v_pk_fma_f32 v[114:115], v[26:27], v[26:27], v[130:131]
	v_mul_f32_e32 v116, v27, v27
	v_pk_fma_f32 v[28:29], v[28:29], v[94:95], v[102:103] op_sel_hi:[1,0,1] neg_lo:[0,0,1] neg_hi:[0,0,1]
	v_pk_add_f32 v[114:115], v[116:117], v[114:115] op_sel_hi:[0,1]
	v_pk_fma_f32 v[102:103], v[28:29], v[28:29], v[114:115]
	v_mul_f32_e32 v94, v29, v29
	v_pk_add_f32 v[102:103], v[94:95], v[102:103] op_sel_hi:[0,1]
	v_pk_fma_f32 v[102:103], v[86:87], v[86:87], v[102:103]
	v_mul_f32_e32 v94, v87, v87
	v_pk_add_f32 v[102:103], v[94:95], v[102:103] op_sel_hi:[0,1]
	v_mov_b32_e32 v94, v102
	s_nop 1
	v_permlane32_swap_b32_e32 v102, v94
	v_add_f32_e32 v94, v102, v94
	v_mov_b32_e32 v102, 0x358637bd
	v_fmamk_f32 v94, v94, 0x3c000000, v102
	s_mov_b32 s2, 0xf800000
	v_mul_f32_e32 v102, 0x4f800000, v94
	v_cmp_gt_f32_e32 vcc, s2, v94
	v_add_f32_e32 v116, 1.0, v117
	v_mul_f32_e32 v70, 0xbfb8aa3b, v68
	v_cndmask_b32_e32 v94, v94, v102, vcc
	v_sqrt_f32_e32 v114, v94
	v_rcp_f32_e32 v102, v116
	v_mul_f32_e32 v71, 0xbfb8aa3b, v69
	v_mul_f32_e32 v58, 0xbfb8aa3b, v56
	v_add_u32_e32 v115, -1, v114
	v_fma_f32 v116, -v115, v114, v94
	v_cmp_ge_f32_e64 s[4:5], 0, v116
	v_add_u32_e32 v116, 1, v114
	v_mul_f32_e32 v59, 0xbfb8aa3b, v57
	v_cndmask_b32_e64 v115, v114, v115, s[4:5]
	v_fma_f32 v114, -v116, v114, v94
	v_mul_f32_e32 v62, 0xbfb8aa3b, v60
	v_mul_f32_e32 v63, 0xbfb8aa3b, v61
	v_cmp_lt_f32_e64 s[4:5], 0, v114
	v_exp_f32_e32 v70, v70
	v_exp_f32_e32 v71, v71
	v_exp_f32_e32 v58, v58
	v_exp_f32_e32 v59, v59
	v_exp_f32_e32 v62, v62
	v_exp_f32_e32 v63, v63
	v_and_b32_e32 v83, 0xffff0000, v83
	v_cndmask_b32_e64 v114, v115, v116, s[4:5]
	v_mul_f32_e32 v117, 0xbfb8aa3b, v83
	v_mul_f32_e32 v115, 0x37800000, v114
	v_exp_f32_e32 v117, v117
	v_cndmask_b32_e32 v114, v114, v115, vcc
	v_cmp_class_f32_e32 vcc, v94, v232
	s_mov_b32 s4, 0x3f4ccccd
	v_add_f32_e32 v48, 1.0, v70
	v_cndmask_b32_e32 v94, v114, v94, vcc
	v_add_f32_e32 v49, 1.0, v71
	v_add_f32_e32 v52, 1.0, v58
	v_add_f32_e32 v53, 1.0, v59
	v_add_f32_e32 v32, 1.0, v62
	v_add_f32_e32 v33, 1.0, v63
	v_div_scale_f32 v130, s[2:3], v94, v94, s4
	v_rcp_f32_e32 v48, v48
	v_rcp_f32_e32 v49, v49
	v_rcp_f32_e32 v52, v52
	v_rcp_f32_e32 v53, v53
	v_rcp_f32_e32 v32, v32
	v_rcp_f32_e32 v33, v33
	v_rcp_f32_e32 v36, v36
	v_rcp_f32_e32 v37, v37
	v_rcp_f32_e32 v42, v42
	v_rcp_f32_e32 v43, v43
	v_rcp_f32_e32 v131, v130
	v_add_f32_e32 v103, 1.0, v117
	v_rcp_f32_e32 v103, v103
	v_add_u32_e32 v0, 0x24800, v0
	ds_read_b128 v[6:9], v0
	ds_read_b128 v[2:5], v0 offset:32
	ds_read_b128 v[64:67], v0 offset:64
	ds_read_b128 v[10:13], v0 offset:96
	v_pk_mul_f32 v[186:187], v[48:49], v[68:69]
	ds_read_b128 v[68:71], v0 offset:128
	ds_read_b128 v[48:51], v0 offset:160
	v_pk_mul_f32 v[206:207], v[52:53], v[56:57]
	ds_read_b128 v[56:59], v0 offset:192
	ds_read_b128 v[52:55], v0 offset:224
	v_pk_mul_f32 v[218:219], v[32:33], v[60:61]
	ds_read_b128 v[60:63], v0 offset:256
	ds_read_b128 v[30:33], v0 offset:288
	v_pk_mul_f32 v[222:223], v[36:37], v[40:41]
	ds_read_b128 v[38:41], v0 offset:320
	ds_read_b128 v[34:37], v0 offset:352
	v_pk_mul_f32 v[224:225], v[42:43], v[14:15]
	ds_read_b128 v[42:45], v0 offset:384
	ds_read_b128 v[14:17], v0 offset:416
	ds_read_b128 v[114:117], v0 offset:448
	ds_read_b128 v[148:151], v0 offset:480
	v_fma_f32 v0, -v130, v131, 1.0
	v_fmac_f32_e32 v131, v0, v131
	v_div_scale_f32 v0, vcc, s4, v94, s4
	v_pk_mul_f32 v[82:83], v[102:103], v[82:83]
	v_mul_f32_e32 v102, v0, v131
	v_fma_f32 v103, -v130, v102, v0
	v_fmac_f32_e32 v102, v103, v131
	v_fma_f32 v0, -v130, v102, v0
	v_div_fmas_f32 v0, v0, v131, v102
	v_div_fixup_f32 v0, v0, v94, s4
	v_pk_mul_f32 v[100:101], v[100:101], v[0:1] op_sel_hi:[1,0]
	v_pk_mul_f32 v[98:99], v[98:99], v[0:1] op_sel_hi:[1,0]
	s_waitcnt lgkmcnt(14)
	v_pk_mul_f32 v[6:7], v[6:7], v[100:101]
	v_pk_mul_f32 v[8:9], v[8:9], v[98:99]
	v_pk_mul_f32 v[6:7], v[106:107], v[6:7]
	v_pk_mul_f32 v[8:9], v[110:111], v[8:9]
	v_cvt_pk_bf16_f32 v6, v6, v7
	v_cvt_pk_bf16_f32 v7, v8, v9
	global_store_dwordx2 v[88:89], v[6:7], off offset:1024
	v_pk_mul_f32 v[6:7], v[112:113], v[0:1] op_sel_hi:[1,0]
	s_nop 0
	v_pk_mul_f32 v[2:3], v[2:3], v[6:7]
	v_pk_mul_f32 v[6:7], v[108:109], v[0:1] op_sel_hi:[1,0]
	v_pk_mul_f32 v[2:3], v[118:119], v[2:3]
	v_pk_mul_f32 v[4:5], v[4:5], v[6:7]
	v_cvt_pk_bf16_f32 v2, v2, v3
	v_pk_mul_f32 v[4:5], v[122:123], v[4:5]
	s_waitcnt vmcnt(1)
	v_lshlrev_b32_e32 v6, 16, v80
	v_cvt_pk_bf16_f32 v3, v4, v5
	global_store_dwordx2 v[88:89], v[2:3], off offset:1040
	v_pk_mul_f32 v[2:3], v[72:73], v[0:1] op_sel_hi:[1,0]
	v_pk_mul_f32 v[4:5], v[74:75], v[0:1] op_sel_hi:[1,0]
	s_waitcnt lgkmcnt(13)
	v_pk_mul_f32 v[2:3], v[64:65], v[2:3]
	v_pk_mul_f32 v[4:5], v[66:67], v[4:5]
	v_pk_mul_f32 v[2:3], v[124:125], v[2:3]
	v_pk_mul_f32 v[4:5], v[128:129], v[4:5]
	v_cvt_pk_bf16_f32 v2, v2, v3
	v_cvt_pk_bf16_f32 v3, v4, v5
	global_store_dwordx2 v[88:89], v[2:3], off offset:1056
	v_pk_mul_f32 v[2:3], v[76:77], v[0:1] op_sel_hi:[1,0]
	v_pk_mul_f32 v[4:5], v[78:79], v[0:1] op_sel_hi:[1,0]
	s_waitcnt lgkmcnt(12)
	v_pk_mul_f32 v[2:3], v[2:3], v[10:11]
	v_pk_mul_f32 v[4:5], v[4:5], v[12:13]
	v_pk_mul_f32 v[2:3], v[134:135], v[2:3]
	v_pk_mul_f32 v[4:5], v[138:139], v[4:5]
	v_cvt_pk_bf16_f32 v2, v2, v3
	v_cvt_pk_bf16_f32 v3, v4, v5
	global_store_dwordx2 v[88:89], v[2:3], off offset:1072
	v_pk_mul_f32 v[2:3], v[140:141], v[0:1] op_sel_hi:[1,0]
	v_pk_mul_f32 v[4:5], v[136:137], v[0:1] op_sel_hi:[1,0]
	s_waitcnt lgkmcnt(11)
	v_pk_mul_f32 v[2:3], v[2:3], v[68:69]
	v_pk_mul_f32 v[4:5], v[4:5], v[70:71]
	v_pk_mul_f32 v[2:3], v[178:179], v[2:3]
	v_pk_mul_f32 v[4:5], v[186:187], v[4:5]
	v_cvt_pk_bf16_f32 v2, v2, v3
	v_cvt_pk_bf16_f32 v3, v4, v5
	global_store_dwordx2 v[88:89], v[2:3], off offset:1088
	v_pk_mul_f32 v[2:3], v[188:189], v[0:1] op_sel_hi:[1,0]
	v_pk_mul_f32 v[4:5], v[184:185], v[0:1] op_sel_hi:[1,0]
	s_waitcnt lgkmcnt(10)
	v_pk_mul_f32 v[2:3], v[2:3], v[48:49]
	v_pk_mul_f32 v[4:5], v[4:5], v[50:51]
	v_pk_mul_f32 v[2:3], v[146:147], v[2:3]
	v_pk_mul_f32 v[4:5], v[194:195], v[4:5]
	v_cvt_pk_bf16_f32 v2, v2, v3
	v_cvt_pk_bf16_f32 v3, v4, v5
	global_store_dwordx2 v[88:89], v[2:3], off offset:1104
	v_pk_mul_f32 v[2:3], v[200:201], v[0:1] op_sel_hi:[1,0]
	v_pk_mul_f32 v[4:5], v[192:193], v[0:1] op_sel_hi:[1,0]
	s_waitcnt lgkmcnt(9)
	v_pk_mul_f32 v[2:3], v[2:3], v[56:57]
	v_pk_mul_f32 v[4:5], v[4:5], v[58:59]
	v_pk_mul_f32 v[2:3], v[132:133], v[2:3]
	v_pk_mul_f32 v[4:5], v[206:207], v[4:5]
	v_cvt_pk_bf16_f32 v2, v2, v3
	v_cvt_pk_bf16_f32 v3, v4, v5
	global_store_dwordx2 v[88:89], v[2:3], off offset:1120
	v_pk_mul_f32 v[2:3], v[210:211], v[0:1] op_sel_hi:[1,0]
	v_pk_mul_f32 v[4:5], v[202:203], v[0:1] op_sel_hi:[1,0]
	s_waitcnt lgkmcnt(8)
	v_pk_mul_f32 v[2:3], v[2:3], v[52:53]
	v_pk_mul_f32 v[4:5], v[4:5], v[54:55]
	v_pk_mul_f32 v[2:3], v[120:121], v[2:3]
	v_pk_mul_f32 v[4:5], v[214:215], v[4:5]
	v_cvt_pk_bf16_f32 v2, v2, v3
	v_cvt_pk_bf16_f32 v3, v4, v5
	global_store_dwordx2 v[88:89], v[2:3], off offset:1136
	v_pk_mul_f32 v[2:3], v[216:217], v[0:1] op_sel_hi:[1,0]
	v_pk_mul_f32 v[4:5], v[212:213], v[0:1] op_sel_hi:[1,0]
	s_waitcnt lgkmcnt(7)
	v_pk_mul_f32 v[2:3], v[2:3], v[60:61]
	v_pk_mul_f32 v[4:5], v[4:5], v[62:63]
	v_pk_mul_f32 v[2:3], v[104:105], v[2:3]
	v_pk_mul_f32 v[4:5], v[218:219], v[4:5]
	v_cvt_pk_bf16_f32 v2, v2, v3
	v_cvt_pk_bf16_f32 v3, v4, v5
	global_store_dwordx2 v[88:89], v[2:3], off offset:1152
	v_pk_mul_f32 v[2:3], v[204:205], v[0:1] op_sel_hi:[1,0]
	v_pk_mul_f32 v[4:5], v[208:209], v[0:1] op_sel_hi:[1,0]
	s_waitcnt lgkmcnt(6)
	v_pk_mul_f32 v[2:3], v[2:3], v[30:31]
	v_pk_mul_f32 v[4:5], v[4:5], v[32:33]
	v_pk_mul_f32 v[2:3], v[96:97], v[2:3]
	v_pk_mul_f32 v[4:5], v[220:221], v[4:5]
	v_cvt_pk_bf16_f32 v2, v2, v3
	v_cvt_pk_bf16_f32 v3, v4, v5
	global_store_dwordx2 v[88:89], v[2:3], off offset:1168
	v_pk_mul_f32 v[2:3], v[190:191], v[0:1] op_sel_hi:[1,0]
	v_pk_mul_f32 v[4:5], v[198:199], v[0:1] op_sel_hi:[1,0]
	s_waitcnt lgkmcnt(5)
	v_pk_mul_f32 v[2:3], v[2:3], v[38:39]
	v_pk_mul_f32 v[4:5], v[4:5], v[40:41]
	v_pk_mul_f32 v[2:3], v[92:93], v[2:3]
	v_pk_mul_f32 v[4:5], v[222:223], v[4:5]
	v_cvt_pk_bf16_f32 v2, v2, v3
	v_cvt_pk_bf16_f32 v3, v4, v5
	global_store_dwordx2 v[88:89], v[2:3], off offset:1184
	v_pk_mul_f32 v[2:3], v[180:181], v[0:1] op_sel_hi:[1,0]
	v_pk_mul_f32 v[4:5], v[46:47], v[0:1] op_sel_hi:[1,0]
	s_waitcnt lgkmcnt(4)
	v_pk_mul_f32 v[2:3], v[2:3], v[34:35]
	v_pk_mul_f32 v[4:5], v[4:5], v[36:37]
	v_pk_mul_f32 v[2:3], v[90:91], v[2:3]
	v_pk_mul_f32 v[4:5], v[182:183], v[4:5]
	v_cvt_pk_bf16_f32 v2, v2, v3
	v_cvt_pk_bf16_f32 v3, v4, v5
	global_store_dwordx2 v[88:89], v[2:3], off offset:1200
	v_pk_mul_f32 v[2:3], v[142:143], v[0:1] op_sel_hi:[1,0]
	v_pk_mul_f32 v[4:5], v[18:19], v[0:1] op_sel_hi:[1,0]
	s_waitcnt lgkmcnt(3)
	v_pk_mul_f32 v[2:3], v[2:3], v[42:43]
	v_pk_mul_f32 v[4:5], v[4:5], v[44:45]
	v_pk_mul_f32 v[2:3], v[144:145], v[2:3]
	v_pk_mul_f32 v[4:5], v[224:225], v[4:5]
	v_cvt_pk_bf16_f32 v2, v2, v3
	v_cvt_pk_bf16_f32 v3, v4, v5
	global_store_dwordx2 v[88:89], v[2:3], off offset:1216
	v_pk_mul_f32 v[2:3], v[20:21], v[0:1] op_sel_hi:[1,0]
	v_pk_mul_f32 v[4:5], v[22:23], v[0:1] op_sel_hi:[1,0]
	s_waitcnt lgkmcnt(2)
	v_pk_mul_f32 v[2:3], v[2:3], v[14:15]
	v_pk_mul_f32 v[4:5], v[4:5], v[16:17]
	v_pk_mul_f32 v[2:3], v[84:85], v[2:3]
	v_pk_mul_f32 v[4:5], v[126:127], v[4:5]
	v_cvt_pk_bf16_f32 v2, v2, v3
	v_cvt_pk_bf16_f32 v3, v4, v5
	global_store_dwordx2 v[88:89], v[2:3], off offset:1232
	v_pk_mul_f32 v[2:3], v[24:25], v[0:1] op_sel_hi:[1,0]
	v_and_b32_e32 v7, 0xffff0000, v80
	s_waitcnt lgkmcnt(1)
	v_pk_mul_f32 v[2:3], v[2:3], v[114:115]
	v_pk_mul_f32 v[4:5], v[26:27], v[0:1] op_sel_hi:[1,0]
	v_pk_mul_f32 v[2:3], v[234:235], v[2:3]
	v_pk_mul_f32 v[4:5], v[4:5], v[116:117]
	v_cvt_pk_bf16_f32 v2, v2, v3
	v_mul_f32_e32 v3, 0xbfb8aa3b, v6
	v_exp_f32_e32 v8, v3
	v_mul_f32_e32 v3, 0xbfb8aa3b, v7
	v_exp_f32_e32 v9, v3
	v_pk_mul_f32 v[4:5], v[82:83], v[4:5]
	s_nop 0
	v_cvt_pk_bf16_f32 v3, v4, v5
	v_add_f32_e32 v4, 1.0, v8
	v_add_f32_e32 v5, 1.0, v9
	v_rcp_f32_e32 v4, v4
	v_rcp_f32_e32 v5, v5
	global_store_dwordx2 v[88:89], v[2:3], off offset:1248
	v_pk_mul_f32 v[2:3], v[28:29], v[0:1] op_sel_hi:[1,0]
	v_pk_mul_f32 v[4:5], v[4:5], v[6:7]
	v_lshlrev_b32_e32 v6, 16, v81
	v_and_b32_e32 v7, 0xffff0000, v81
	v_mul_f32_e32 v8, 0xbfb8aa3b, v6
	v_mul_f32_e32 v9, 0xbfb8aa3b, v7
	v_exp_f32_e32 v8, v8
	v_exp_f32_e32 v9, v9
	s_waitcnt lgkmcnt(0)
	v_pk_mul_f32 v[2:3], v[2:3], v[148:149]
	s_nop 0
	v_pk_mul_f32 v[2:3], v[4:5], v[2:3]
	v_add_f32_e32 v4, 1.0, v8
	v_add_f32_e32 v5, 1.0, v9
	v_rcp_f32_e32 v4, v4
	v_rcp_f32_e32 v5, v5
	v_pk_mul_f32 v[8:9], v[86:87], v[0:1] op_sel_hi:[1,0]
	v_cvt_pk_bf16_f32 v2, v2, v3
	v_pk_mul_f32 v[8:9], v[8:9], v[150:151]
	v_pk_mul_f32 v[4:5], v[4:5], v[6:7]
	s_nop 0
	v_pk_mul_f32 v[4:5], v[4:5], v[8:9]
	s_nop 0
	v_cvt_pk_bf16_f32 v3, v4, v5
	global_store_dwordx2 v[88:89], v[2:3], off offset:1264
	s_branch .LBB0_299
